# phase-1 epilogue exchange steps: four LDS reads in flight (distinct registers, counted waits) before the stores
# speedup vs baseline: 1.0150x; 1.0013x over previous
.LBB0_135:
	v_lshlrev_b32_e32 v2, 4, v1
	v_ashrrev_i32_e32 v4, 3, v11
	v_and_b32_e32 v2, 0x70, v2
	v_mov_b32_e32 v3, v0
	v_lshl_add_u64 v[6:7], s[2:3], 0, v[2:3]
	v_lshrrev_b32_e32 v3, 2, v4
	v_xor_b32_e32 v3, v3, v1
	v_add_u32_e32 v12, s52, v4
	v_lshlrev_b32_e32 v3, 4, v3
	v_lshlrev_b32_e32 v2, 7, v12
	v_and_b32_e32 v3, 0x70, v3
	s_waitcnt lgkmcnt(0)
	s_barrier
	v_add3_u32 v2, s53, v2, v3
	ds_read_b128 v[150:153], v2
	v_mul_lo_u32 v8, s4, v12
	v_mov_b32_e32 v9, v0
	v_lshl_add_u64 v[166:167], v[8:9], 1, v[6:7]
	s_lshl_b32 s0, s4, 3
	v_add_u32_e32 v8, s0, v8
	v_lshl_add_u64 v[168:169], v[8:9], 1, v[6:7]
	v_add_u32_e32 v2, 8, v12
	v_lshlrev_b32_e32 v3, 7, v2
	v_lshrrev_b32_e32 v2, 2, v2
	v_xor_b32_e32 v2, v2, v1
	v_lshlrev_b32_e32 v2, 4, v2
	v_and_b32_e32 v2, 0x70, v2
	v_add3_u32 v2, s53, v3, v2
	ds_read_b128 v[154:157], v2
	v_add_u32_e32 v8, s0, v8
	s_nop 1
	v_add_u32_e32 v2, 16, v12
	v_lshlrev_b32_e32 v3, 7, v2
	v_lshrrev_b32_e32 v2, 2, v2
	v_xor_b32_e32 v2, v2, v1
	v_lshlrev_b32_e32 v2, 4, v2
	v_and_b32_e32 v2, 0x70, v2
	v_add3_u32 v2, s53, v3, v2
	ds_read_b128 v[158:161], v2
	v_lshl_add_u64 v[170:171], v[8:9], 1, v[6:7]
	v_add_u32_e32 v8, s0, v8
	v_lshl_add_u64 v[172:173], v[8:9], 1, v[6:7]
	s_nop 1
	v_add_u32_e32 v2, 24, v12
	v_lshlrev_b32_e32 v3, 7, v2
	v_lshrrev_b32_e32 v2, 2, v2
	v_xor_b32_e32 v1, v2, v1
	v_lshlrev_b32_e32 v1, 4, v1
	v_and_b32_e32 v1, 0x70, v1
	v_add3_u32 v1, s53, v3, v1
	ds_read_b128 v[162:165], v1
	s_waitcnt lgkmcnt(3)
	global_store_dwordx4 v[166:167], v[150:153], off
	s_waitcnt lgkmcnt(2)
	global_store_dwordx4 v[168:169], v[154:157], off
	s_waitcnt lgkmcnt(1)
	global_store_dwordx4 v[170:171], v[158:161], off
	s_waitcnt lgkmcnt(0)
	global_store_dwordx4 v[172:173], v[162:165], off
	s_waitcnt lgkmcnt(0)
	s_barrier

.LBB0_286:
	s_waitcnt lgkmcnt(0)
	s_barrier
	v_and_b32_e32 v131, 15, v142
	v_readlane_b32 s12, v251, 51
	v_cmp_gt_u32_e32 vcc, 8, v131
	v_readlane_b32 s13, v251, 52
	s_or_b64 s[80:81], s[12:13], vcc
	s_and_saveexec_b64 s[12:13], s[80:81]
	s_cbranch_execz .LBB0_288
	v_lshrrev_b32_e32 v131, 3, v131
	v_mul_u32_u24_e32 v131, s76, v131
	v_and_b32_e32 v135, s69, v142
	v_lshlrev_b32_e32 v131, 1, v131
	v_lshl_or_b32 v136, v135, 4, v131
	v_ashrrev_i32_e32 v131, 4, v133
	v_add_u32_e32 v135, s75, v131
	v_xor_b32_e32 v131, v131, v142
	v_mov_b32_e32 v137, v0
	v_lshlrev_b32_e32 v131, 4, v131
	v_lshl_add_u64 v[140:141], s[2:3], 0, v[136:137]
	v_lshlrev_b32_e32 v136, 8, v135
	v_and_b32_e32 v131, 0xf0, v131
	v_add3_u32 v131, s53, v131, v136
	ds_read_b128 v[150:153], v131
	v_mul_lo_u32 v144, s65, v135
	v_mov_b32_e32 v145, v0
	v_lshl_add_u64 v[166:167], v[144:145], 1, v[140:141]
	v_add_u32_e32 v131, 4, v135
	s_lshl_b32 s2, s65, 2
	v_add_u32_e32 v144, s2, v144
	v_lshlrev_b32_e32 v136, 8, v131
	v_xor_b32_e32 v131, v131, v142
	v_lshlrev_b32_e32 v131, 4, v131
	v_and_b32_e32 v131, 0xf0, v131
	v_add3_u32 v131, s53, v131, v136
	ds_read_b128 v[154:157], v131
	v_lshl_add_u64 v[168:169], v[144:145], 1, v[140:141]
	v_add_u32_e32 v131, 8, v135
	v_add_u32_e32 v144, s2, v144
	v_lshl_add_u64 v[170:171], v[144:145], 1, v[140:141]
	s_nop 0
	v_lshlrev_b32_e32 v136, 8, v131
	v_xor_b32_e32 v131, v131, v142
	v_lshlrev_b32_e32 v131, 4, v131
	v_and_b32_e32 v131, 0xf0, v131
	v_add3_u32 v131, s53, v131, v136
	ds_read_b128 v[158:161], v131
	v_add_u32_e32 v131, 12, v135
	v_lshlrev_b32_e32 v135, 8, v131
	v_xor_b32_e32 v131, v131, v142
	v_lshlrev_b32_e32 v131, 4, v131
	v_and_b32_e32 v131, 0xf0, v131
	v_add3_u32 v131, s53, v131, v135
	s_nop 0
	v_add_u32_e32 v136, s2, v144
	v_mov_b32_e32 v137, v0
	v_lshl_add_u64 v[172:173], v[136:137], 1, v[140:141]
	ds_read_b128 v[162:165], v131
	s_waitcnt lgkmcnt(3)
	global_store_dwordx4 v[166:167], v[150:153], off
	s_waitcnt lgkmcnt(2)
	global_store_dwordx4 v[168:169], v[154:157], off
	s_waitcnt lgkmcnt(1)
	global_store_dwordx4 v[170:171], v[158:161], off
	s_waitcnt lgkmcnt(0)
	global_store_dwordx4 v[172:173], v[162:165], off

.LBB0_302:
	v_lshlrev_b32_e32 v98, 4, v142
	v_ashrrev_i32_e32 v100, 3, v133
	v_and_b32_e32 v98, 0x70, v98
	v_mov_b32_e32 v99, v0
	v_lshl_add_u64 v[102:103], s[2:3], 0, v[98:99]
	v_lshrrev_b32_e32 v99, 2, v100
	v_xor_b32_e32 v99, v99, v142
	v_add_u32_e32 v108, s52, v100
	v_lshlrev_b32_e32 v99, 4, v99
	v_lshlrev_b32_e32 v98, 7, v108
	v_and_b32_e32 v99, 0x70, v99
	s_waitcnt lgkmcnt(0)
	s_barrier
	v_add3_u32 v98, s53, v98, v99
	ds_read_b128 v[150:153], v98
	v_mul_lo_u32 v104, s69, v108
	v_mov_b32_e32 v105, v0
	v_lshl_add_u64 v[166:167], v[104:105], 1, v[102:103]
	s_lshl_b32 s2, s69, 3
	v_add_u32_e32 v104, s2, v104
	v_lshl_add_u64 v[168:169], v[104:105], 1, v[102:103]
	v_add_u32_e32 v98, 8, v108
	v_lshlrev_b32_e32 v99, 7, v98
	v_lshrrev_b32_e32 v98, 2, v98
	v_xor_b32_e32 v98, v98, v142
	v_lshlrev_b32_e32 v98, 4, v98
	v_and_b32_e32 v98, 0x70, v98
	v_add3_u32 v98, s53, v99, v98
	ds_read_b128 v[154:157], v98
	v_add_u32_e32 v104, s2, v104
	s_nop 1
	v_add_u32_e32 v98, 16, v108
	v_lshlrev_b32_e32 v99, 7, v98
	v_lshrrev_b32_e32 v98, 2, v98
	v_xor_b32_e32 v98, v98, v142
	v_lshlrev_b32_e32 v98, 4, v98
	v_and_b32_e32 v98, 0x70, v98
	v_add3_u32 v98, s53, v99, v98
	ds_read_b128 v[158:161], v98
	v_lshl_add_u64 v[170:171], v[104:105], 1, v[102:103]
	v_add_u32_e32 v104, s2, v104
	v_lshl_add_u64 v[172:173], v[104:105], 1, v[102:103]
	s_nop 1
	v_add_u32_e32 v98, 24, v108
	v_lshlrev_b32_e32 v99, 7, v98
	v_lshrrev_b32_e32 v98, 2, v98
	v_xor_b32_e32 v98, v98, v142
	v_lshlrev_b32_e32 v98, 4, v98
	v_and_b32_e32 v98, 0x70, v98
	v_add3_u32 v98, s53, v99, v98
	ds_read_b128 v[162:165], v98
	s_waitcnt lgkmcnt(3)
	global_store_dwordx4 v[166:167], v[150:153], off
	s_waitcnt lgkmcnt(2)
	global_store_dwordx4 v[168:169], v[154:157], off
	s_waitcnt lgkmcnt(1)
	global_store_dwordx4 v[170:171], v[158:161], off
	s_waitcnt lgkmcnt(0)
	global_store_dwordx4 v[172:173], v[162:165], off
	s_waitcnt lgkmcnt(0)
	s_barrier

.LBB0_336:
	v_and_b32_e32 v103, s24, v101
	v_lshlrev_b32_e32 v104, 4, v103
	v_ashrrev_i32_e32 v103, 4, v99
	v_add_u32_e32 v114, s75, v103
	v_xor_b32_e32 v103, v103, v101
	v_mov_b32_e32 v105, v0
	v_lshlrev_b32_e32 v103, 4, v103
	v_lshl_add_u64 v[108:109], s[48:49], 0, v[104:105]
	v_lshlrev_b32_e32 v104, 8, v114
	v_and_b32_e32 v103, 0xf0, v103
	s_waitcnt lgkmcnt(0)
	s_barrier
	v_add3_u32 v103, s53, v103, v104
	ds_read_b128 v[150:153], v103
	v_mul_lo_u32 v110, s5, v114
	v_mov_b32_e32 v111, v0
	v_lshl_add_u64 v[166:167], v[110:111], 1, v[108:109]
	v_add_u32_e32 v103, 4, v114
	s_lshl_b32 s5, s5, 2
	v_add_u32_e32 v110, s5, v110
	v_lshlrev_b32_e32 v104, 8, v103
	v_xor_b32_e32 v103, v103, v101
	v_lshlrev_b32_e32 v103, 4, v103
	v_and_b32_e32 v103, 0xf0, v103
	v_add3_u32 v103, s53, v103, v104
	ds_read_b128 v[154:157], v103
	v_lshl_add_u64 v[168:169], v[110:111], 1, v[108:109]
	v_add_u32_e32 v103, 8, v114
	v_add_u32_e32 v110, s5, v110
	v_lshl_add_u64 v[170:171], v[110:111], 1, v[108:109]
	s_nop 0
	v_lshlrev_b32_e32 v104, 8, v103
	v_xor_b32_e32 v103, v103, v101
	v_lshlrev_b32_e32 v103, 4, v103
	v_and_b32_e32 v103, 0xf0, v103
	v_add3_u32 v103, s53, v103, v104
	ds_read_b128 v[158:161], v103
	v_add_u32_e32 v103, 12, v114
	s_nop 1
	v_add_u32_e32 v104, s5, v110
	v_mov_b32_e32 v105, v0
	v_lshl_add_u64 v[172:173], v[104:105], 1, v[108:109]
	v_lshlrev_b32_e32 v104, 8, v103
	v_xor_b32_e32 v103, v103, v101
	v_lshlrev_b32_e32 v103, 4, v103
	v_and_b32_e32 v103, 0xf0, v103
	v_add3_u32 v103, s53, v103, v104
	ds_read_b128 v[162:165], v103
	s_waitcnt lgkmcnt(3)
	global_store_dwordx4 v[166:167], v[150:153], off
	s_waitcnt lgkmcnt(2)
	global_store_dwordx4 v[168:169], v[154:157], off
	s_waitcnt lgkmcnt(1)
	global_store_dwordx4 v[170:171], v[158:161], off
	s_waitcnt lgkmcnt(0)
	global_store_dwordx4 v[172:173], v[162:165], off
	s_waitcnt lgkmcnt(0)
	s_barrier
	s_cmp_lt_i32 s50, 8
	s_cbranch_scc0 .LBB0_307

.LBB0_352:
	v_lshlrev_b32_e32 v66, 4, v101
	v_ashrrev_i32_e32 v68, 3, v99
	v_and_b32_e32 v66, 0x70, v66
	v_mov_b32_e32 v67, v0
	v_lshl_add_u64 v[70:71], s[48:49], 0, v[66:67]
	v_lshrrev_b32_e32 v67, 2, v68
	v_xor_b32_e32 v67, v67, v101
	v_add_u32_e32 v76, s52, v68
	v_lshlrev_b32_e32 v67, 4, v67
	v_lshlrev_b32_e32 v66, 7, v76
	v_and_b32_e32 v67, 0x70, v67
	s_waitcnt lgkmcnt(0)
	s_barrier
	v_add3_u32 v66, s53, v66, v67
	ds_read_b128 v[150:153], v66
	v_mul_lo_u32 v72, s5, v76
	v_mov_b32_e32 v73, v0
	v_lshl_add_u64 v[166:167], v[72:73], 1, v[70:71]
	s_lshl_b32 s5, s5, 3
	v_add_u32_e32 v72, s5, v72
	v_lshl_add_u64 v[168:169], v[72:73], 1, v[70:71]
	v_add_u32_e32 v66, 8, v76
	v_lshlrev_b32_e32 v67, 7, v66
	v_lshrrev_b32_e32 v66, 2, v66
	v_xor_b32_e32 v66, v66, v101
	v_lshlrev_b32_e32 v66, 4, v66
	v_and_b32_e32 v66, 0x70, v66
	v_add3_u32 v66, s53, v67, v66
	ds_read_b128 v[154:157], v66
	v_add_u32_e32 v72, s5, v72
	s_nop 1
	v_add_u32_e32 v66, 16, v76
	v_lshlrev_b32_e32 v67, 7, v66
	v_lshrrev_b32_e32 v66, 2, v66
	v_xor_b32_e32 v66, v66, v101
	v_lshlrev_b32_e32 v66, 4, v66
	v_and_b32_e32 v66, 0x70, v66
	v_add3_u32 v66, s53, v67, v66
	ds_read_b128 v[158:161], v66
	v_lshl_add_u64 v[170:171], v[72:73], 1, v[70:71]
	v_add_u32_e32 v72, s5, v72
	v_lshl_add_u64 v[172:173], v[72:73], 1, v[70:71]
	s_nop 1
	v_add_u32_e32 v66, 24, v76
	v_lshlrev_b32_e32 v67, 7, v66
	v_lshrrev_b32_e32 v66, 2, v66
	v_xor_b32_e32 v66, v66, v101
	v_lshlrev_b32_e32 v66, 4, v66
	v_and_b32_e32 v66, 0x70, v66
	v_add3_u32 v66, s53, v67, v66
	ds_read_b128 v[162:165], v66
	s_waitcnt lgkmcnt(3)
	global_store_dwordx4 v[166:167], v[150:153], off
	s_waitcnt lgkmcnt(2)
	global_store_dwordx4 v[168:169], v[154:157], off
	s_waitcnt lgkmcnt(1)
	global_store_dwordx4 v[170:171], v[158:161], off
	s_waitcnt lgkmcnt(0)
	global_store_dwordx4 v[172:173], v[162:165], off
	s_waitcnt lgkmcnt(0)
	s_barrier

.LBB0_418:
	s_waitcnt lgkmcnt(0)
	s_barrier
	v_and_b32_e32 v70, 15, v78
	v_readlane_b32 s36, v251, 51
	v_cmp_gt_u32_e32 vcc, 8, v70
	v_readlane_b32 s37, v251, 52
	s_or_b64 s[58:59], s[36:37], vcc
	s_and_saveexec_b64 s[46:47], s[58:59]
	s_mov_b32 s74, 0xc2fc0000
	s_mov_b32 s75, s76
	s_cbranch_execz .LBB0_420
	v_lshrrev_b32_e32 v70, 3, v70
	v_mul_u32_u24_e32 v70, s57, v70
	v_and_b32_e32 v71, s54, v78
	v_lshlrev_b32_e32 v70, 1, v70
	v_lshl_or_b32 v70, v71, 4, v70
	v_mov_b32_e32 v71, v0
	v_lshl_add_u64 v[74:75], s[70:71], 0, v[70:71]
	v_ashrrev_i32_e32 v70, 4, v67
	v_add_u32_e32 v79, s75, v70
	v_xor_b32_e32 v70, v70, v78
	v_lshlrev_b32_e32 v70, 4, v70
	v_lshlrev_b32_e32 v71, 8, v79
	v_and_b32_e32 v70, 0xf0, v70
	v_add3_u32 v70, s53, v70, v71
	ds_read_b128 v[150:153], v70
	v_mul_lo_u32 v76, s51, v79
	v_mov_b32_e32 v77, v0
	v_lshl_add_u64 v[166:167], v[76:77], 1, v[74:75]
	s_lshl_b32 s19, s51, 2
	v_add_u32_e32 v76, s19, v76
	v_lshl_add_u64 v[168:169], v[76:77], 1, v[74:75]
	v_add_u32_e32 v70, 4, v79
	v_lshlrev_b32_e32 v71, 8, v70
	v_xor_b32_e32 v70, v70, v78
	v_lshlrev_b32_e32 v70, 4, v70
	v_and_b32_e32 v70, 0xf0, v70
	v_add3_u32 v70, s53, v70, v71
	ds_read_b128 v[154:157], v70
	v_add_u32_e32 v76, s19, v76
	s_nop 1
	v_add_u32_e32 v70, 8, v79
	v_lshlrev_b32_e32 v71, 8, v70
	v_xor_b32_e32 v70, v70, v78
	v_lshlrev_b32_e32 v70, 4, v70
	v_and_b32_e32 v70, 0xf0, v70
	v_add3_u32 v70, s53, v70, v71
	ds_read_b128 v[158:161], v70
	v_lshl_add_u64 v[170:171], v[76:77], 1, v[74:75]
	s_nop 1
	v_add_u32_e32 v72, 12, v79
	v_add_u32_e32 v70, s19, v76
	v_mov_b32_e32 v71, v0
	v_lshl_add_u64 v[172:173], v[70:71], 1, v[74:75]
	v_xor_b32_e32 v71, v72, v78
	v_lshlrev_b32_e32 v71, 4, v71
	v_lshlrev_b32_e32 v70, 8, v72
	v_and_b32_e32 v71, 0xf0, v71
	v_add3_u32 v70, s53, v71, v70
	ds_read_b128 v[162:165], v70
	s_waitcnt lgkmcnt(3)
	global_store_dwordx4 v[166:167], v[150:153], off
	s_waitcnt lgkmcnt(2)
	global_store_dwordx4 v[168:169], v[154:157], off
	s_waitcnt lgkmcnt(1)
	global_store_dwordx4 v[170:171], v[158:161], off
	s_waitcnt lgkmcnt(0)
	global_store_dwordx4 v[172:173], v[162:165], off

.LBB0_433:
	v_lshlrev_b32_e32 v10, 4, v78
	v_ashrrev_i32_e32 v12, 3, v67
	v_and_b32_e32 v10, 0x70, v10
	v_mov_b32_e32 v11, v0
	v_lshl_add_u64 v[22:23], s[6:7], 0, v[10:11]
	v_lshrrev_b32_e32 v11, 2, v12
	v_xor_b32_e32 v11, v11, v78
	v_add_u32_e32 v32, s52, v12
	v_lshlrev_b32_e32 v11, 4, v11
	v_lshlrev_b32_e32 v10, 7, v32
	v_and_b32_e32 v11, 0x70, v11
	s_waitcnt lgkmcnt(0)
	s_barrier
	v_add3_u32 v10, s53, v10, v11
	ds_read_b128 v[150:153], v10
	v_mul_lo_u32 v24, s5, v32
	v_mov_b32_e32 v25, v0
	v_lshl_add_u64 v[166:167], v[24:25], 1, v[22:23]
	s_lshl_b32 s5, s5, 3
	v_add_u32_e32 v24, s5, v24
	v_lshl_add_u64 v[168:169], v[24:25], 1, v[22:23]
	v_add_u32_e32 v10, 8, v32
	v_lshlrev_b32_e32 v11, 7, v10
	v_lshrrev_b32_e32 v10, 2, v10
	v_xor_b32_e32 v10, v10, v78
	v_lshlrev_b32_e32 v10, 4, v10
	v_and_b32_e32 v10, 0x70, v10
	v_add3_u32 v10, s53, v11, v10
	ds_read_b128 v[154:157], v10
	v_add_u32_e32 v24, s5, v24
	s_nop 1
	v_add_u32_e32 v10, 16, v32
	v_lshlrev_b32_e32 v11, 7, v10
	v_lshrrev_b32_e32 v10, 2, v10
	v_xor_b32_e32 v10, v10, v78
	v_lshlrev_b32_e32 v10, 4, v10
	v_and_b32_e32 v10, 0x70, v10
	v_add3_u32 v10, s53, v11, v10
	ds_read_b128 v[158:161], v10
	v_lshl_add_u64 v[170:171], v[24:25], 1, v[22:23]
	v_add_u32_e32 v24, s5, v24
	v_lshl_add_u64 v[172:173], v[24:25], 1, v[22:23]
	s_nop 1
	v_add_u32_e32 v10, 24, v32
	v_lshlrev_b32_e32 v11, 7, v10
	v_lshrrev_b32_e32 v10, 2, v10
	v_xor_b32_e32 v10, v10, v78
	v_lshlrev_b32_e32 v10, 4, v10
	v_and_b32_e32 v10, 0x70, v10
	v_add3_u32 v10, s53, v11, v10
	ds_read_b128 v[162:165], v10
	s_waitcnt lgkmcnt(3)
	global_store_dwordx4 v[166:167], v[150:153], off
	s_waitcnt lgkmcnt(2)
	global_store_dwordx4 v[168:169], v[154:157], off
	s_waitcnt lgkmcnt(1)
	global_store_dwordx4 v[170:171], v[158:161], off
	s_waitcnt lgkmcnt(0)
	global_store_dwordx4 v[172:173], v[162:165], off
	s_waitcnt lgkmcnt(0)
	s_barrier

.LBB0_467:
	v_and_b32_e32 v13, s5, v1
	v_lshlrev_b32_e32 v22, 4, v13
	v_ashrrev_i32_e32 v13, 4, v11
	v_add_u32_e32 v44, s75, v13
	v_xor_b32_e32 v13, v13, v1
	v_mov_b32_e32 v23, v0
	v_lshlrev_b32_e32 v13, 4, v13
	v_lshl_add_u64 v[30:31], s[2:3], 0, v[22:23]
	v_lshlrev_b32_e32 v22, 8, v44
	v_and_b32_e32 v13, 0xf0, v13
	s_waitcnt lgkmcnt(0)
	s_barrier
	v_add3_u32 v13, s53, v13, v22
	ds_read_b128 v[150:153], v13
	v_mul_lo_u32 v32, s4, v44
	v_mov_b32_e32 v33, v0
	v_lshl_add_u64 v[166:167], v[32:33], 1, v[30:31]
	v_add_u32_e32 v13, 4, v44
	s_lshl_b32 s2, s4, 2
	v_add_u32_e32 v32, s2, v32
	v_lshlrev_b32_e32 v22, 8, v13
	v_xor_b32_e32 v13, v13, v1
	v_lshlrev_b32_e32 v13, 4, v13
	v_and_b32_e32 v13, 0xf0, v13
	v_add3_u32 v13, s53, v13, v22
	ds_read_b128 v[154:157], v13
	v_lshl_add_u64 v[168:169], v[32:33], 1, v[30:31]
	v_add_u32_e32 v13, 8, v44
	v_add_u32_e32 v32, s2, v32
	v_lshl_add_u64 v[170:171], v[32:33], 1, v[30:31]
	s_nop 0
	v_lshlrev_b32_e32 v22, 8, v13
	v_xor_b32_e32 v13, v13, v1
	v_lshlrev_b32_e32 v13, 4, v13
	v_and_b32_e32 v13, 0xf0, v13
	v_add3_u32 v13, s53, v13, v22
	ds_read_b128 v[158:161], v13
	v_add_u32_e32 v13, 12, v44
	s_nop 1
	v_add_u32_e32 v22, s2, v32
	v_mov_b32_e32 v23, v0
	v_lshl_add_u64 v[172:173], v[22:23], 1, v[30:31]
	v_lshlrev_b32_e32 v22, 8, v13
	v_xor_b32_e32 v13, v13, v1
	v_lshlrev_b32_e32 v13, 4, v13
	v_and_b32_e32 v13, 0xf0, v13
	v_add3_u32 v13, s53, v13, v22
	ds_read_b128 v[162:165], v13
	s_waitcnt lgkmcnt(3)
	global_store_dwordx4 v[166:167], v[150:153], off
	s_waitcnt lgkmcnt(2)
	global_store_dwordx4 v[168:169], v[154:157], off
	s_waitcnt lgkmcnt(1)
	global_store_dwordx4 v[170:171], v[158:161], off
	s_waitcnt lgkmcnt(0)
	global_store_dwordx4 v[172:173], v[162:165], off
	s_waitcnt lgkmcnt(0)
	s_barrier
	s_cmp_lt_i32 s50, 8
	s_cbranch_scc0 .LBB0_438
